# v17 plus weight-conversion tile loads issued together (16 in flight) instead of one at a time
# speedup vs baseline: 1.0100x; 1.0100x over previous
;     ...
;         const int nl = tid & 63;
;         const int sc = map_col(d.map, nt * 64 + nl);
; #pragma unroll 4
;         for (int i = 0; i < 16; ++i) {
;           const int kl = (tid >> 6) + 4 * i;
;           const int k = kt * 64 + kl;
;           float v = 0.f;
;           if (sc >= 0) v = d.src[(size_t)k * d.ldsrc + sc];
;           if (d.rowscale) v *= d.rowscale[k];
;           T[kl * 65 + nl] = v;
;         }
.LBB0_83:
	s_lshl_b32 s84, s84, 6
	s_ashr_i32 s85, s84, 31
	v_cmp_lt_i32_e64 s[8:9], -1, v8
	v_lshl_add_u64 v[30:31], v[8:9], 2, s[70:71]
	v_lshl_add_u64 v[32:33], v[20:21], 0, s[84:85]
	v_lshl_add_u32 v8, s87, 6, v20
	s_lshl_b32 s10, s86, 6
	v_subrev_u32_e32 v8, s10, v8
	v_lshl_add_u64 v[32:33], v[32:33], 2, s[82:83]
	s_mov_b32 s20, 0
	v_mov_b32_e32 v39, v36
	s_and_b64 vcc, exec, s[78:79]
	s_cbranch_vccnz .LBB0_85
	v_mov_b32_e32 v80, 0
	v_mov_b32_e32 v81, 0
	v_mov_b32_e32 v82, 0
	v_mov_b32_e32 v83, 0
	v_mov_b32_e32 v84, 0
	v_mov_b32_e32 v85, 0
	v_mov_b32_e32 v86, 0
	v_mov_b32_e32 v87, 0
	v_mov_b32_e32 v88, 0
	v_mov_b32_e32 v89, 0
	v_mov_b32_e32 v90, 0
	v_mov_b32_e32 v91, 0
	v_mov_b32_e32 v92, 0
	v_mov_b32_e32 v93, 0
	v_mov_b32_e32 v94, 0
	v_mov_b32_e32 v95, 0
	s_and_saveexec_b64 s[10:11], s[8:9]
	s_cbranch_execz .Lcv1_noload
	v_ashrrev_i32_e32 v35, 31, v8
	v_mul_lo_u32 v42, s73, v8
	v_mul_lo_u32 v43, s72, v35
	v_mad_u64_u32 v[40:41], s[22:23], s72, v8, 0
	v_add3_u32 v41, v41, v43, v42
	v_lshl_add_u64 v[40:41], v[40:41], 2, v[30:31]
	s_lshl_b64 s[100:101], s[72:73], 4
	global_load_dword v80, v[40:41], off
	v_lshl_add_u64 v[40:41], v[40:41], 0, s[100:101]
	global_load_dword v81, v[40:41], off
	v_lshl_add_u64 v[40:41], v[40:41], 0, s[100:101]
	global_load_dword v82, v[40:41], off
	v_lshl_add_u64 v[40:41], v[40:41], 0, s[100:101]
	global_load_dword v83, v[40:41], off
	v_lshl_add_u64 v[40:41], v[40:41], 0, s[100:101]
	global_load_dword v84, v[40:41], off
	v_lshl_add_u64 v[40:41], v[40:41], 0, s[100:101]
	global_load_dword v85, v[40:41], off
	v_lshl_add_u64 v[40:41], v[40:41], 0, s[100:101]
	global_load_dword v86, v[40:41], off
	v_lshl_add_u64 v[40:41], v[40:41], 0, s[100:101]
	global_load_dword v87, v[40:41], off
	v_lshl_add_u64 v[40:41], v[40:41], 0, s[100:101]
	global_load_dword v88, v[40:41], off
	v_lshl_add_u64 v[40:41], v[40:41], 0, s[100:101]
	global_load_dword v89, v[40:41], off
	v_lshl_add_u64 v[40:41], v[40:41], 0, s[100:101]
	global_load_dword v90, v[40:41], off
	v_lshl_add_u64 v[40:41], v[40:41], 0, s[100:101]
	global_load_dword v91, v[40:41], off
	v_lshl_add_u64 v[40:41], v[40:41], 0, s[100:101]
	global_load_dword v92, v[40:41], off
	v_lshl_add_u64 v[40:41], v[40:41], 0, s[100:101]
	global_load_dword v93, v[40:41], off
	v_lshl_add_u64 v[40:41], v[40:41], 0, s[100:101]
	global_load_dword v94, v[40:41], off
	v_lshl_add_u64 v[40:41], v[40:41], 0, s[100:101]
	global_load_dword v95, v[40:41], off
.Lcv1_noload:
	s_or_b64 exec, exec, s[10:11]
	s_waitcnt vmcnt(0)
	ds_write_b32 v39, v80
	ds_write_b32 v39, v81 offset:1040
	ds_write_b32 v39, v82 offset:2080
	ds_write_b32 v39, v83 offset:3120
	ds_write_b32 v39, v84 offset:4160
	ds_write_b32 v39, v85 offset:5200
	ds_write_b32 v39, v86 offset:6240
	ds_write_b32 v39, v87 offset:7280
	ds_write_b32 v39, v88 offset:8320
	ds_write_b32 v39, v89 offset:9360
	ds_write_b32 v39, v90 offset:10400
	ds_write_b32 v39, v91 offset:11440
	ds_write_b32 v39, v92 offset:12480
	ds_write_b32 v39, v93 offset:13520
	ds_write_b32 v39, v94 offset:14560
	ds_write_b32 v39, v95 offset:15600
	v_add_u32_e32 v39, 0x4100, v39
	s_mov_b32 s20, 64
	s_branch .LBB0_101
	s_branch .LBB0_85

;     ...
;         const int nl = tid & 63;
;         const int sc = map_col(d.map, nt * 64 + nl);
; #pragma unroll 4
;         for (int i = 0; i < 16; ++i) {
;           const int kl = (tid >> 6) + 4 * i;
;           const int k = kt * 64 + kl;
;           float v = 0.f;
;           if (sc >= 0) v = d.src[(size_t)k * d.ldsrc + sc];
;           if (d.rowscale) v *= d.rowscale[k];
;           T[kl * 65 + nl] = v;
;         }
.LBB0_1366:
	s_lshl_b32 s8, s45, 6
	s_ashr_i32 s9, s8, 31
	v_cmp_lt_i32_e64 s[42:43], -1, v0
	v_lshl_add_u64 v[26:27], v[0:1], 2, s[52:53]
	v_lshl_add_u64 v[28:29], v[18:19], 0, s[8:9]
	v_lshl_add_u32 v0, s44, 6, v18
	s_lshl_b32 s1, s1, 6
	v_subrev_u32_e32 v0, s1, v0
	v_lshl_add_u64 v[28:29], v[28:29], 2, s[6:7]
	s_mov_b32 s1, 0
	v_mov_b32_e32 v37, v33
	s_and_b64 vcc, exec, s[86:87]
	s_cbranch_vccnz .LBB0_1368
	v_mov_b32_e32 v80, 0
	v_mov_b32_e32 v81, 0
	v_mov_b32_e32 v82, 0
	v_mov_b32_e32 v83, 0
	v_mov_b32_e32 v84, 0
	v_mov_b32_e32 v85, 0
	v_mov_b32_e32 v86, 0
	v_mov_b32_e32 v87, 0
	v_mov_b32_e32 v88, 0
	v_mov_b32_e32 v89, 0
	v_mov_b32_e32 v90, 0
	v_mov_b32_e32 v91, 0
	v_mov_b32_e32 v92, 0
	v_mov_b32_e32 v93, 0
	v_mov_b32_e32 v94, 0
	v_mov_b32_e32 v95, 0
	s_and_saveexec_b64 s[44:45], s[42:43]
	s_cbranch_execz .Lcv2_noload
	v_ashrrev_i32_e32 v31, 31, v0
	v_mul_lo_u32 v40, s95, v0
	v_mul_lo_u32 v41, s94, v31
	v_mad_u64_u32 v[38:39], vcc, s94, v0, 0
	v_add3_u32 v39, v39, v41, v40
	v_lshl_add_u64 v[38:39], v[38:39], 2, v[26:27]
	s_lshl_b64 s[100:101], s[94:95], 4
	global_load_dword v80, v[38:39], off
	v_lshl_add_u64 v[38:39], v[38:39], 0, s[100:101]
	global_load_dword v81, v[38:39], off
	v_lshl_add_u64 v[38:39], v[38:39], 0, s[100:101]
	global_load_dword v82, v[38:39], off
	v_lshl_add_u64 v[38:39], v[38:39], 0, s[100:101]
	global_load_dword v83, v[38:39], off
	v_lshl_add_u64 v[38:39], v[38:39], 0, s[100:101]
	global_load_dword v84, v[38:39], off
	v_lshl_add_u64 v[38:39], v[38:39], 0, s[100:101]
	global_load_dword v85, v[38:39], off
	v_lshl_add_u64 v[38:39], v[38:39], 0, s[100:101]
	global_load_dword v86, v[38:39], off
	v_lshl_add_u64 v[38:39], v[38:39], 0, s[100:101]
	global_load_dword v87, v[38:39], off
	v_lshl_add_u64 v[38:39], v[38:39], 0, s[100:101]
	global_load_dword v88, v[38:39], off
	v_lshl_add_u64 v[38:39], v[38:39], 0, s[100:101]
	global_load_dword v89, v[38:39], off
	v_lshl_add_u64 v[38:39], v[38:39], 0, s[100:101]
	global_load_dword v90, v[38:39], off
	v_lshl_add_u64 v[38:39], v[38:39], 0, s[100:101]
	global_load_dword v91, v[38:39], off
	v_lshl_add_u64 v[38:39], v[38:39], 0, s[100:101]
	global_load_dword v92, v[38:39], off
	v_lshl_add_u64 v[38:39], v[38:39], 0, s[100:101]
	global_load_dword v93, v[38:39], off
	v_lshl_add_u64 v[38:39], v[38:39], 0, s[100:101]
	global_load_dword v94, v[38:39], off
	v_lshl_add_u64 v[38:39], v[38:39], 0, s[100:101]
	global_load_dword v95, v[38:39], off
.Lcv2_noload:
	s_or_b64 exec, exec, s[44:45]
	s_waitcnt vmcnt(0)
	ds_write_b32 v37, v80
	ds_write_b32 v37, v81 offset:1040
	ds_write_b32 v37, v82 offset:2080
	ds_write_b32 v37, v83 offset:3120
	ds_write_b32 v37, v84 offset:4160
	ds_write_b32 v37, v85 offset:5200
	ds_write_b32 v37, v86 offset:6240
	ds_write_b32 v37, v87 offset:7280
	ds_write_b32 v37, v88 offset:8320
	ds_write_b32 v37, v89 offset:9360
	ds_write_b32 v37, v90 offset:10400
	ds_write_b32 v37, v91 offset:11440
	ds_write_b32 v37, v92 offset:12480
	ds_write_b32 v37, v93 offset:13520
	ds_write_b32 v37, v94 offset:14560
	ds_write_b32 v37, v95 offset:15600
	v_add_u32_e32 v37, 0x4100, v37
	s_mov_b32 s1, 64
	s_branch .LBB0_1384
	s_branch .LBB0_1368

; __global__ void __launch_bounds__(256, 2) mega(Params pk) {
	.amdhsa_kernel _Z4mega6Params
		.amdhsa_group_segment_fixed_size 16
		.amdhsa_private_segment_fixed_size 0
		.amdhsa_kernarg_size 528
		.amdhsa_user_sgpr_count 2
		.amdhsa_user_sgpr_dispatch_ptr 0
		.amdhsa_user_sgpr_queue_ptr 0
		.amdhsa_user_sgpr_kernarg_segment_ptr 1
		.amdhsa_user_sgpr_dispatch_id 0
		.amdhsa_user_sgpr_kernarg_preload_length 0
		.amdhsa_user_sgpr_kernarg_preload_offset 0
		.amdhsa_user_sgpr_private_segment_size 0
		.amdhsa_uses_dynamic_stack 0
		.amdhsa_enable_private_segment 0
		.amdhsa_system_sgpr_workgroup_id_x 1
		.amdhsa_system_sgpr_workgroup_id_y 0
		.amdhsa_system_sgpr_workgroup_id_z 0
		.amdhsa_system_sgpr_workgroup_info 0
		.amdhsa_system_vgpr_workitem_id 2
		.amdhsa_next_free_vgpr 252
		.amdhsa_next_free_sgpr 102
		.amdhsa_accum_offset 252
		.amdhsa_reserve_vcc 1
		.amdhsa_float_round_mode_32 0
		.amdhsa_float_round_mode_16_64 0
		.amdhsa_float_denorm_mode_32 3
		.amdhsa_float_denorm_mode_16_64 3
		.amdhsa_dx10_clamp 1
		.amdhsa_ieee_mode 1
		.amdhsa_fp16_overflow 0
		.amdhsa_tg_split 0
		.amdhsa_exception_fp_ieee_invalid_op 0
		.amdhsa_exception_fp_denorm_src 0
		.amdhsa_exception_fp_ieee_div_zero 0
		.amdhsa_exception_fp_ieee_overflow 0
		.amdhsa_exception_fp_ieee_underflow 0
		.amdhsa_exception_fp_ieee_inexact 0
		.amdhsa_exception_int_div_zero 0
	.end_amdhsa_kernel

; __global__ void __launch_bounds__(256, 2) mega(Params pk) {
amdhsa.kernels:
  - .agpr_count:     0
    .args:
      - .offset:         0
        .size:           272
        .value_kind:     by_value
      - .offset:         272
        .size:           4
        .value_kind:     hidden_block_count_x
      - .offset:         276
        .size:           4
        .value_kind:     hidden_block_count_y
      - .offset:         280
        .size:           4
        .value_kind:     hidden_block_count_z
      - .offset:         284
        .size:           2
        .value_kind:     hidden_group_size_x
      - .offset:         286
        .size:           2
        .value_kind:     hidden_group_size_y
      - .offset:         288
        .size:           2
        .value_kind:     hidden_group_size_z
      - .offset:         290
        .size:           2
        .value_kind:     hidden_remainder_x
      - .offset:         292
        .size:           2
        .value_kind:     hidden_remainder_y
      - .offset:         294
        .size:           2
        .value_kind:     hidden_remainder_z
      - .offset:         312
        .size:           8
        .value_kind:     hidden_global_offset_x
      - .offset:         320
        .size:           8
        .value_kind:     hidden_global_offset_y
      - .offset:         328
        .size:           8
        .value_kind:     hidden_global_offset_z
      - .offset:         336
        .size:           2
        .value_kind:     hidden_grid_dims
      - .offset:         360
        .size:           8
        .value_kind:     hidden_multigrid_sync_arg
      - .offset:         392
        .size:           4
        .value_kind:     hidden_dynamic_lds_size
    .group_segment_fixed_size: 16
    .kernarg_segment_align: 8
    .kernarg_segment_size: 528
    .language:       OpenCL C
    .language_version:
      - 2
      - 0
    .max_flat_workgroup_size: 256
    .name:           _Z4mega6Params
    .private_segment_fixed_size: 0
    .sgpr_count:     108
    .sgpr_spill_count: 149
    .symbol:         _Z4mega6Params.kd
    .uniform_work_group_size: 1
    .uses_dynamic_stack: false
    .vgpr_count:     252
    .vgpr_spill_count: 0
    .wavefront_size: 64
